# P1/P6 unit header: full vmcnt(0) store drain removed; the K-loop's counted waits retire the epilogue stores in order
# baseline (speedup 1.0000x reference)
.LBB0_130:
	s_ashr_i32 s23, s22, 31
	s_lshl_b64 s[24:25], s[22:23], 20
	s_add_u32 s24, s90, s24
	s_addc_u32 s25, s91, s25
	s_and_b64 s[26:27], s[0:1], exec
	s_cselect_b32 s23, s25, s31
	s_cselect_b32 s51, s24, s30
	s_ashr_i32 s21, s20, 31
	s_lshl_b64 s[26:27], s[20:21], 20
	s_add_u32 s26, s2, s26
	s_addc_u32 s27, s3, s27
	s_and_b64 s[36:37], s[0:1], exec
	s_cselect_b32 s21, s27, s35
	s_cselect_b32 s52, s26, s34
	s_add_u32 s30, s30, 0x80080
	s_addc_u32 s31, s31, 0
	s_add_u32 s53, s34, 0x100
	v_mov_b32_e32 v0, 0
	s_addc_u32 s54, s35, 0
	s_mov_b32 s55, -2
	v_mov_b32_e32 v1, v0
	v_mov_b64_e32 v[2:3], 0
	v_mov_b64_e32 v[4:5], 0
	v_mov_b64_e32 v[6:7], 0
	v_mov_b64_e32 v[16:17], 0
	v_mov_b64_e32 v[18:19], 0
	v_mov_b64_e32 v[20:21], 0
	v_mov_b64_e32 v[22:23], 0
	v_mov_b64_e32 v[32:33], 0
	v_mov_b64_e32 v[34:35], 0
	v_mov_b64_e32 v[36:37], 0
	v_mov_b64_e32 v[38:39], 0
	v_mov_b64_e32 v[48:49], 0
	v_mov_b64_e32 v[50:51], 0
	v_mov_b64_e32 v[52:53], 0
	v_mov_b64_e32 v[54:55], 0
	v_mov_b64_e32 v[8:9], 0
	v_mov_b64_e32 v[10:11], 0
	v_mov_b64_e32 v[12:13], 0
	v_mov_b64_e32 v[14:15], 0
	v_mov_b64_e32 v[24:25], 0
	v_mov_b64_e32 v[26:27], 0
	v_mov_b64_e32 v[28:29], 0
	v_mov_b64_e32 v[30:31], 0
	v_mov_b64_e32 v[40:41], 0
	v_mov_b64_e32 v[42:43], 0
	v_mov_b64_e32 v[44:45], 0
	v_mov_b64_e32 v[46:47], 0
	v_mov_b64_e32 v[56:57], 0
	v_mov_b64_e32 v[58:59], 0
	v_mov_b64_e32 v[60:61], 0
	v_mov_b64_e32 v[62:63], 0
	v_mov_b64_e32 v[64:65], 0
	v_mov_b64_e32 v[66:67], 0
	v_mov_b64_e32 v[68:69], 0
	v_mov_b64_e32 v[70:71], 0
	v_mov_b64_e32 v[80:81], 0
	v_mov_b64_e32 v[82:83], 0
	v_mov_b64_e32 v[84:85], 0
	v_mov_b64_e32 v[86:87], 0
	v_mov_b64_e32 v[96:97], 0
	v_mov_b64_e32 v[98:99], 0
	v_mov_b64_e32 v[100:101], 0
	v_mov_b64_e32 v[102:103], 0
	v_mov_b64_e32 v[112:113], 0
	v_mov_b64_e32 v[114:115], 0
	v_mov_b64_e32 v[116:117], 0
	v_mov_b64_e32 v[118:119], 0
	v_mov_b64_e32 v[72:73], 0
	v_mov_b64_e32 v[74:75], 0
	v_mov_b64_e32 v[76:77], 0
	v_mov_b64_e32 v[78:79], 0
	v_mov_b64_e32 v[88:89], 0
	v_mov_b64_e32 v[90:91], 0
	v_mov_b64_e32 v[92:93], 0
	v_mov_b64_e32 v[94:95], 0
	v_mov_b64_e32 v[104:105], 0
	v_mov_b64_e32 v[106:107], 0
	v_mov_b64_e32 v[108:109], 0
	v_mov_b64_e32 v[110:111], 0
	v_mov_b64_e32 v[120:121], 0
	v_mov_b64_e32 v[122:123], 0
	v_mov_b64_e32 v[124:125], 0
	v_mov_b64_e32 v[126:127], 0

.LBB0_670:
	s_ashr_i32 s19, s18, 31
	s_lshl_b64 s[20:21], s[18:19], 20
	s_add_u32 s20, s3, s20
	s_addc_u32 s21, s33, s21
	s_and_b64 s[22:23], s[0:1], exec
	s_cselect_b32 s19, s21, s27
	s_cselect_b32 s49, s20, s26
	s_ashr_i32 s17, s16, 31
	s_lshl_b64 s[22:23], s[16:17], 20
	s_add_u32 s22, s34, s22
	s_addc_u32 s23, s35, s23
	s_and_b64 s[30:31], s[0:1], exec
	s_cselect_b32 s17, s23, s29
	s_cselect_b32 s50, s22, s28
	s_add_u32 s26, s26, 0x80080
	s_addc_u32 s27, s27, 0
	s_add_u32 s51, s28, 0x100
	v_mov_b32_e32 v4, 0
	s_addc_u32 s52, s29, 0
	s_mov_b32 s53, -2
	v_mov_b32_e32 v5, v4
	v_mov_b64_e32 v[6:7], 0
	v_mov_b64_e32 v[12:13], 0
	v_mov_b64_e32 v[14:15], 0
	v_mov_b64_e32 v[24:25], 0
	v_mov_b64_e32 v[26:27], 0
	v_mov_b64_e32 v[28:29], 0
	v_mov_b64_e32 v[30:31], 0
	v_mov_b64_e32 v[40:41], 0
	v_mov_b64_e32 v[42:43], 0
	v_mov_b64_e32 v[44:45], 0
	v_mov_b64_e32 v[46:47], 0
	v_mov_b64_e32 v[56:57], 0
	v_mov_b64_e32 v[58:59], 0
	v_mov_b64_e32 v[60:61], 0
	v_mov_b64_e32 v[62:63], 0
	v_mov_b64_e32 v[0:1], 0
	v_mov_b64_e32 v[2:3], 0
	v_mov_b64_e32 v[8:9], 0
	v_mov_b64_e32 v[10:11], 0
	v_mov_b64_e32 v[16:17], 0
	v_mov_b64_e32 v[18:19], 0
	v_mov_b64_e32 v[20:21], 0
	v_mov_b64_e32 v[22:23], 0
	v_mov_b64_e32 v[32:33], 0
	v_mov_b64_e32 v[34:35], 0
	v_mov_b64_e32 v[36:37], 0
	v_mov_b64_e32 v[38:39], 0
	v_mov_b64_e32 v[48:49], 0
	v_mov_b64_e32 v[50:51], 0
	v_mov_b64_e32 v[52:53], 0
	v_mov_b64_e32 v[54:55], 0
	v_mov_b64_e32 v[72:73], 0
	v_mov_b64_e32 v[74:75], 0
	v_mov_b64_e32 v[76:77], 0
	v_mov_b64_e32 v[78:79], 0
	v_mov_b64_e32 v[88:89], 0
	v_mov_b64_e32 v[90:91], 0
	v_mov_b64_e32 v[92:93], 0
	v_mov_b64_e32 v[94:95], 0
	v_mov_b64_e32 v[104:105], 0
	v_mov_b64_e32 v[106:107], 0
	v_mov_b64_e32 v[108:109], 0
	v_mov_b64_e32 v[110:111], 0
	v_mov_b64_e32 v[120:121], 0
	v_mov_b64_e32 v[122:123], 0
	v_mov_b64_e32 v[124:125], 0
	v_mov_b64_e32 v[126:127], 0
	v_mov_b64_e32 v[64:65], 0
	v_mov_b64_e32 v[66:67], 0
	v_mov_b64_e32 v[68:69], 0
	v_mov_b64_e32 v[70:71], 0
	v_mov_b64_e32 v[80:81], 0
	v_mov_b64_e32 v[82:83], 0
	v_mov_b64_e32 v[84:85], 0
	v_mov_b64_e32 v[86:87], 0
	v_mov_b64_e32 v[96:97], 0
	v_mov_b64_e32 v[98:99], 0
	v_mov_b64_e32 v[100:101], 0
	v_mov_b64_e32 v[102:103], 0
	v_mov_b64_e32 v[112:113], 0
	v_mov_b64_e32 v[114:115], 0
	v_mov_b64_e32 v[116:117], 0
	v_mov_b64_e32 v[118:119], 0
